# pc2_first_k_iteration_peeled_c0
# baseline (speedup 1.0000x reference)
; #define PG8_STAGE(bufoff, gbase, voff) do { _Pragma("unroll") for (int _i = 0; _i < 2; ++_i) \
;         __builtin_amdgcn_global_load_lds((const unsigned*)((const char*)(gbase) + (voff)[_i]), (LAS unsigned*)(lds + (bufoff) + ldsw + _i * 8192), 16, 0, 0); } while (0)
; #define PG8_LDA(dst, b, h) do { _Pragma("unroll") for (int m = 0; m < 4; ++m) _Pragma("unroll") for (int k = 0; k < 2; ++k) dst[m][k] = *(const LAS bf16x8*)(lds + PG8_SA(b, h) + aoff + m * 2048 + k * 1024); } while (0)
; #define PG8_LDB(dst, b, h) do { _Pragma("unroll") for (int n = 0; n < 2; ++n) _Pragma("unroll") for (int k = 0; k < 2; ++k) dst[n][k] = *(const LAS bf16x8*)(lds + PG8_SB(b, h) + boff + n * 2048 + k * 1024); } while (0)
; #define PG8_WAIT_V(n) asm volatile("s_waitcnt vmcnt(" #n ")" ::: "memory")
; #define PG8_WAIT_L(n) asm volatile("s_waitcnt lgkmcnt(" #n ")" ::: "memory")
; #define PG8_BAR __builtin_amdgcn_s_barrier()
; template <class Epi, class Sched>
; __device__ __forceinline__ void gemm_phase(LAS unsigned char* lds, const Sched& S, const Epi& E, bool natural = false) {
;     ...
;         const char* nA = cA; const char* nB = cB; if (has_next) S.ptrs(nxt, nA, nB);
;         for (int t = 0; t < nt; t += 2) {
;             const bool last = (t == nt - 2);
;             const char* a1 = cA + (size_t)(t + 1) * kstep;
;             const char* a2 = last ? nA : cA + (size_t)(t + 2) * kstep; const char* b2 = last ? nB : cB + (size_t)(t + 2) * kstep;
;             const char* a3 = a2 + kstep; const char* b3 = b2 + kstep;
;             if constexpr (Epi::MIDHOOK) { if (t == nt / 2) E.mid(acc, cur, wr, wc, fr, fq); }
;             PG8_LDB(B0, 0, 0); PG8_LDB(B1, 0, 1); PG8_SCHED; PG8_LDA(At, 0, 0); PG8_STAGE(PG8_SA(1, 1), a1 + hstep, voffA);
;             PG8_WAIT_V(8); PG8_WAIT_L(0); PG8_BAR; PG8_MMA(0, 0, At, B0); PG8_MMA(0, 1, At, B1); PG8_BAR; PG8_SCHED;
;             PG8_LDA(At, 0, 1); PG8_STAGE(PG8_SB(0, 0), b2, voffB0); PG8_STAGE(PG8_SB(0, 1), b2, voffB1); PG8_STAGE(PG8_SA(0, 0), a2, voffA);
;             PG8_WAIT_V(8); PG8_WAIT_L(0); PG8_BAR; PG8_MMA(1, 0, At, B0); PG8_MMA(1, 1, At, B1); PG8_BAR; PG8_SCHED;
;     ...
;         for (int a = 0; a < 2; ++a)
; #pragma unroll
;             for (int b = 0; b < 2; ++b)
; #pragma unroll
;                 for (int m = 0; m < 4; ++m)
; #pragma unroll
;                     for (int n = 0; n < 2; ++n) acc[a][b][m][n] = (f32x4){0.f, 0.f, 0.f, 0.f};
.LBB0_563:
	s_ashr_i32 s15, s14, 31
	s_ashr_i32 s13, s12, 31
	s_lshl_b64 s[16:17], s[14:15], 19
	s_lshl_b64 s[18:19], s[12:13], 19
	s_add_u32 s16, s3, s16
	s_addc_u32 s17, s28, s17
	s_add_u32 s18, s29, s18
	s_addc_u32 s19, s30, s19
	s_and_b64 s[24:25], s[0:1], exec
	s_cselect_b32 s13, s17, s21
	s_cselect_b32 s15, s16, s20
	s_cselect_b32 s26, s19, s23
	s_cselect_b32 s27, s18, s22
	s_add_u32 s20, s20, 0x40080
	s_addc_u32 s21, s21, 0
	s_add_u32 s54, s22, 0x100
	s_addc_u32 s55, s23, 0
	s_mov_b32 s56, -2
	ds_read_b128 v[150:153], v156
	ds_read_b128 v[160:163], v156 offset:1024
	ds_read_b128 v[164:167], v156 offset:2048
	ds_read_b128 v[168:171], v156 offset:3072
	ds_read_b128 v[172:175], v157
	ds_read_b128 v[176:179], v157 offset:1024
	ds_read_b128 v[180:183], v157 offset:2048
	ds_read_b128 v[184:187], v157 offset:3072
	s_add_u32 s22, s20, 0xfffc0080
	s_addc_u32 s23, s21, -1
	s_cmp_eq_u32 s56, 12
	s_cselect_b32 s25, s13, s23
	s_cselect_b32 s24, s15, s22
	s_cselect_b32 s23, s26, s55
	s_cselect_b32 s22, s27, s54
	v_lshl_add_u64 v[220:221], s[20:21], 0, v[142:143]
	s_add_i32 m0, s35, 0xc000
	ds_read_b128 v[188:191], v158
	ds_read_b128 v[192:195], v158 offset:1024
	ds_read_b128 v[196:199], v158 offset:2048
	ds_read_b128 v[200:203], v158 offset:3072
	ds_read_b128 v[204:207], v158 offset:4096
	ds_read_b128 v[208:211], v158 offset:5120
	ds_read_b128 v[212:215], v158 offset:6144
	ds_read_b128 v[216:219], v158 offset:7168
	global_load_lds_dwordx4 v[220:221], off
	v_lshl_add_u64 v[220:221], s[20:21], 0, v[144:145]
	s_add_i32 m0, s35, 0xe000
	s_nop 0
	global_load_lds_dwordx4 v[220:221], off
	s_waitcnt vmcnt(8)
	s_waitcnt lgkmcnt(0)
	s_barrier
	s_setprio 1
	s_waitcnt lgkmcnt(0)
	v_mfma_f32_16x16x32_bf16 v[124:127], v[150:153], v[188:191], 0
	v_mfma_f32_16x16x32_bf16 v[120:123], v[164:167], v[188:191], 0
	v_mfma_f32_16x16x32_bf16 v[116:119], v[150:153], v[196:199], 0
	v_mfma_f32_16x16x32_bf16 v[112:115], v[164:167], v[196:199], 0
	v_mfma_f32_16x16x32_bf16 v[104:107], v[150:153], v[204:207], 0
	v_mfma_f32_16x16x32_bf16 v[96:99], v[164:167], v[204:207], 0
	v_mfma_f32_16x16x32_bf16 v[88:91], v[150:153], v[212:215], 0
	v_mfma_f32_16x16x32_bf16 v[80:83], v[164:167], v[212:215], 0
	v_mfma_f32_16x16x32_bf16 v[124:127], v[160:163], v[192:195], v[124:127]
	v_mfma_f32_16x16x32_bf16 v[120:123], v[168:171], v[192:195], v[120:123]
	v_mfma_f32_16x16x32_bf16 v[116:119], v[160:163], v[200:203], v[116:119]
	v_mfma_f32_16x16x32_bf16 v[112:115], v[168:171], v[200:203], v[112:115]
	v_mfma_f32_16x16x32_bf16 v[104:107], v[160:163], v[208:211], v[104:107]
	v_mfma_f32_16x16x32_bf16 v[96:99], v[168:171], v[208:211], v[96:99]
	v_mfma_f32_16x16x32_bf16 v[88:91], v[160:163], v[216:219], v[88:91]
	v_mfma_f32_16x16x32_bf16 v[80:83], v[168:171], v[216:219], v[80:83]
	s_setprio 0
	s_setprio 1
	v_mfma_f32_16x16x32_bf16 v[108:111], v[172:175], v[188:191], 0
	v_mfma_f32_16x16x32_bf16 v[100:103], v[180:183], v[188:191], 0
	v_mfma_f32_16x16x32_bf16 v[92:95], v[172:175], v[196:199], 0
	v_mfma_f32_16x16x32_bf16 v[84:87], v[180:183], v[196:199], 0
	v_mfma_f32_16x16x32_bf16 v[76:79], v[172:175], v[204:207], 0
	v_mfma_f32_16x16x32_bf16 v[72:75], v[180:183], v[204:207], 0
	v_mfma_f32_16x16x32_bf16 v[68:71], v[172:175], v[212:215], 0
	v_mfma_f32_16x16x32_bf16 v[64:67], v[180:183], v[212:215], 0
	v_mfma_f32_16x16x32_bf16 v[108:111], v[176:179], v[192:195], v[108:111]
	v_mfma_f32_16x16x32_bf16 v[100:103], v[184:187], v[192:195], v[100:103]
	v_mfma_f32_16x16x32_bf16 v[92:95], v[176:179], v[200:203], v[92:95]
	v_mfma_f32_16x16x32_bf16 v[84:87], v[184:187], v[200:203], v[84:87]
	v_mfma_f32_16x16x32_bf16 v[76:79], v[176:179], v[208:211], v[76:79]
	v_mfma_f32_16x16x32_bf16 v[72:75], v[184:187], v[208:211], v[72:75]
	v_mfma_f32_16x16x32_bf16 v[68:71], v[176:179], v[216:219], v[68:71]
	v_mfma_f32_16x16x32_bf16 v[64:67], v[184:187], v[216:219], v[64:67]
	s_setprio 0
	s_barrier
	s_add_i32 s57, s44, s31
	v_lshl_add_u64 v[220:221], s[22:23], 0, v[136:137]
	s_mov_b32 m0, s57
	ds_read_b128 v[188:191], v158 offset:16384
	ds_read_b128 v[192:195], v158 offset:17408
	ds_read_b128 v[196:199], v158 offset:18432
	ds_read_b128 v[200:203], v158 offset:19456
	ds_read_b128 v[204:207], v158 offset:20480
	ds_read_b128 v[208:211], v158 offset:21504
	ds_read_b128 v[212:215], v158 offset:22528
	ds_read_b128 v[216:219], v158 offset:23552
	global_load_lds_dwordx4 v[220:221], off
	v_lshl_add_u64 v[222:223], s[22:23], 0, v[130:131]
	s_add_i32 m0, s57, 0x2000
	s_add_i32 s57, s45, s31
	global_load_lds_dwordx4 v[222:223], off
	v_lshl_add_u64 v[224:225], s[22:23], 0, v[134:135]
	s_mov_b32 m0, s57
	v_lshl_add_u64 v[226:227], s[24:25], 0, v[132:133]
	global_load_lds_dwordx4 v[224:225], off
	v_lshl_add_u64 v[224:225], s[22:23], 0, v[128:129]
	s_add_i32 m0, s57, 0x2000
	s_nop 0
	global_load_lds_dwordx4 v[224:225], off
	v_lshl_add_u64 v[224:225], s[24:25], 0, v[138:139]
	s_mov_b32 m0, s35
	s_nop 0
	global_load_lds_dwordx4 v[224:225], off
	s_mov_b32 m0, s36
	s_nop 0
	global_load_lds_dwordx4 v[226:227], off
	s_waitcnt vmcnt(8)
	s_waitcnt lgkmcnt(0)
	s_barrier
; #define PG8_STAGE(bufoff, gbase, voff) do { _Pragma("unroll") for (int _i = 0; _i < 2; ++_i) \
;         __builtin_amdgcn_global_load_lds((const unsigned*)((const char*)(gbase) + (voff)[_i]), (LAS unsigned*)(lds + (bufoff) + ldsw + _i * 8192), 16, 0, 0); } while (0)
; #define PG8_LDA(dst, b, h) do { _Pragma("unroll") for (int m = 0; m < 4; ++m) _Pragma("unroll") for (int k = 0; k < 2; ++k) dst[m][k] = *(const LAS bf16x8*)(lds + PG8_SA(b, h) + aoff + m * 2048 + k * 1024); } while (0)
; #define PG8_LDB(dst, b, h) do { _Pragma("unroll") for (int n = 0; n < 2; ++n) _Pragma("unroll") for (int k = 0; k < 2; ++k) dst[n][k] = *(const LAS bf16x8*)(lds + PG8_SB(b, h) + boff + n * 2048 + k * 1024); } while (0)
; #define PG8_MMA(ai, bj, At, Bt) do { __builtin_amdgcn_s_setprio(1); _Pragma("unroll") for (int m = 0; m < 4; ++m) _Pragma("unroll") for (int n = 0; n < 2; ++n) _Pragma("unroll") for (int k = 0; k < 2; ++k) \
;         acc[ai][bj][m][n] = __builtin_amdgcn_mfma_f32_16x16x32_bf16(Bt[n][k], At[m][k], acc[ai][bj][m][n], 0, 0, 0); __builtin_amdgcn_s_setprio(0); } while (0)
; #define PG8_WAIT_V(n) asm volatile("s_waitcnt vmcnt(" #n ")" ::: "memory")
; #define PG8_WAIT_L(n) asm volatile("s_waitcnt lgkmcnt(" #n ")" ::: "memory")
; #define PG8_BAR __builtin_amdgcn_s_barrier()
; #define PG8_SCHED __builtin_amdgcn_sched_barrier(0)
; template <class Epi, class Sched>
; __device__ __forceinline__ void gemm_phase(LAS unsigned char* lds, const Sched& S, const Epi& E, bool natural = false) {
;     ...
;             PG8_WAIT_V(8); PG8_WAIT_L(0); PG8_BAR; PG8_MMA(1, 0, At, B0); PG8_MMA(1, 1, At, B1); PG8_BAR; PG8_SCHED;
;             PG8_LDB(B0, 1, 0); PG8_LDB(B1, 1, 1); PG8_SCHED; PG8_LDA(At, 1, 0); PG8_STAGE(PG8_SA(0, 1), a2 + hstep, voffA);
;             PG8_WAIT_V(8); PG8_WAIT_L(0); PG8_BAR; PG8_MMA(0, 0, At, B0); PG8_MMA(0, 1, At, B1); PG8_BAR; PG8_SCHED;
	s_setprio 1
	s_waitcnt lgkmcnt(0)
	v_mfma_f32_16x16x32_bf16 v[60:63], v[150:153], v[188:191], 0
	v_mfma_f32_16x16x32_bf16 v[56:59], v[164:167], v[188:191], 0
	v_mfma_f32_16x16x32_bf16 v[52:55], v[150:153], v[196:199], 0
	v_mfma_f32_16x16x32_bf16 v[48:51], v[164:167], v[196:199], 0
	v_mfma_f32_16x16x32_bf16 v[44:47], v[150:153], v[204:207], 0
	v_mfma_f32_16x16x32_bf16 v[32:35], v[164:167], v[204:207], 0
	v_mfma_f32_16x16x32_bf16 v[20:23], v[150:153], v[212:215], 0
	v_mfma_f32_16x16x32_bf16 v[8:11], v[164:167], v[212:215], 0
	v_mfma_f32_16x16x32_bf16 v[60:63], v[160:163], v[192:195], v[60:63]
	v_mfma_f32_16x16x32_bf16 v[56:59], v[168:171], v[192:195], v[56:59]
	v_mfma_f32_16x16x32_bf16 v[52:55], v[160:163], v[200:203], v[52:55]
	v_mfma_f32_16x16x32_bf16 v[48:51], v[168:171], v[200:203], v[48:51]
	v_mfma_f32_16x16x32_bf16 v[44:47], v[160:163], v[208:211], v[44:47]
	v_mfma_f32_16x16x32_bf16 v[32:35], v[168:171], v[208:211], v[32:35]
	v_mfma_f32_16x16x32_bf16 v[20:23], v[160:163], v[216:219], v[20:23]
	v_mfma_f32_16x16x32_bf16 v[8:11], v[168:171], v[216:219], v[8:11]
	s_setprio 0
	s_setprio 1
	v_mfma_f32_16x16x32_bf16 v[40:43], v[172:175], v[188:191], 0
	v_mfma_f32_16x16x32_bf16 v[36:39], v[180:183], v[188:191], 0
	v_mfma_f32_16x16x32_bf16 v[28:31], v[172:175], v[196:199], 0
	v_mfma_f32_16x16x32_bf16 v[24:27], v[180:183], v[196:199], 0
	v_mfma_f32_16x16x32_bf16 v[16:19], v[172:175], v[204:207], 0
	v_mfma_f32_16x16x32_bf16 v[12:15], v[180:183], v[204:207], 0
	v_mfma_f32_16x16x32_bf16 v[4:7], v[172:175], v[212:215], 0
	v_mfma_f32_16x16x32_bf16 v[0:3], v[180:183], v[212:215], 0
	v_mfma_f32_16x16x32_bf16 v[40:43], v[176:179], v[192:195], v[40:43]
	v_mfma_f32_16x16x32_bf16 v[36:39], v[184:187], v[192:195], v[36:39]
	v_mfma_f32_16x16x32_bf16 v[28:31], v[176:179], v[200:203], v[28:31]
	v_mfma_f32_16x16x32_bf16 v[24:27], v[184:187], v[200:203], v[24:27]
	v_mfma_f32_16x16x32_bf16 v[16:19], v[176:179], v[208:211], v[16:19]
	v_mfma_f32_16x16x32_bf16 v[12:15], v[184:187], v[208:211], v[12:15]
	v_mfma_f32_16x16x32_bf16 v[4:7], v[176:179], v[216:219], v[4:7]
	v_mfma_f32_16x16x32_bf16 v[0:3], v[184:187], v[216:219], v[0:3]
	s_setprio 0
	s_barrier
	s_add_i32 s57, 0, 0x18000
	v_add_u32_e32 v140, s57, v154
	s_add_i32 s58, 0, 0x1c000
	ds_read_b128 v[150:153], v140
	ds_read_b128 v[160:163], v140 offset:1024
	ds_read_b128 v[164:167], v140 offset:2048
	ds_read_b128 v[168:171], v140 offset:3072
	v_add_u32_e32 v140, s58, v154
	ds_read_b128 v[172:175], v140
	ds_read_b128 v[176:179], v140 offset:1024
	ds_read_b128 v[180:183], v140 offset:2048
	ds_read_b128 v[184:187], v140 offset:3072
	s_add_u32 s24, s24, 0x40000
	s_addc_u32 s25, s25, 0
	s_mov_b32 m0, s37
	v_lshl_add_u64 v[228:229], s[24:25], 0, v[138:139]
	ds_read_b128 v[188:191], v158 offset:32768
	ds_read_b128 v[192:195], v158 offset:33792
	ds_read_b128 v[196:199], v158 offset:34816
	ds_read_b128 v[200:203], v158 offset:35840
	ds_read_b128 v[204:207], v158 offset:36864
	ds_read_b128 v[208:211], v158 offset:37888
	ds_read_b128 v[212:215], v158 offset:38912
	ds_read_b128 v[216:219], v158 offset:39936
	global_load_lds_dwordx4 v[228:229], off
	v_lshl_add_u64 v[228:229], s[24:25], 0, v[132:133]
	s_mov_b32 m0, s38
	s_nop 0
	global_load_lds_dwordx4 v[228:229], off
	s_waitcnt vmcnt(8)
	s_waitcnt lgkmcnt(0)
	s_barrier
	s_setprio 1
	s_waitcnt lgkmcnt(0)
	v_mfma_f32_16x16x32_bf16 v[124:127], v[150:153], v[188:191], v[124:127]
	v_mfma_f32_16x16x32_bf16 v[120:123], v[164:167], v[188:191], v[120:123]
	v_mfma_f32_16x16x32_bf16 v[116:119], v[150:153], v[196:199], v[116:119]
	v_mfma_f32_16x16x32_bf16 v[112:115], v[164:167], v[196:199], v[112:115]
	v_mfma_f32_16x16x32_bf16 v[104:107], v[150:153], v[204:207], v[104:107]
	v_mfma_f32_16x16x32_bf16 v[96:99], v[164:167], v[204:207], v[96:99]
	v_mfma_f32_16x16x32_bf16 v[88:91], v[150:153], v[212:215], v[88:91]
	v_mfma_f32_16x16x32_bf16 v[80:83], v[164:167], v[212:215], v[80:83]
	v_mfma_f32_16x16x32_bf16 v[124:127], v[160:163], v[192:195], v[124:127]
	v_mfma_f32_16x16x32_bf16 v[120:123], v[168:171], v[192:195], v[120:123]
	v_mfma_f32_16x16x32_bf16 v[116:119], v[160:163], v[200:203], v[116:119]
	v_mfma_f32_16x16x32_bf16 v[112:115], v[168:171], v[200:203], v[112:115]
	v_mfma_f32_16x16x32_bf16 v[104:107], v[160:163], v[208:211], v[104:107]
	v_mfma_f32_16x16x32_bf16 v[96:99], v[168:171], v[208:211], v[96:99]
	v_mfma_f32_16x16x32_bf16 v[88:91], v[160:163], v[216:219], v[88:91]
	v_mfma_f32_16x16x32_bf16 v[80:83], v[168:171], v[216:219], v[80:83]
	s_setprio 0
	s_setprio 1
	v_mfma_f32_16x16x32_bf16 v[108:111], v[172:175], v[188:191], v[108:111]
	v_mfma_f32_16x16x32_bf16 v[100:103], v[180:183], v[188:191], v[100:103]
	v_mfma_f32_16x16x32_bf16 v[92:95], v[172:175], v[196:199], v[92:95]
	v_mfma_f32_16x16x32_bf16 v[84:87], v[180:183], v[196:199], v[84:87]
	v_mfma_f32_16x16x32_bf16 v[76:79], v[172:175], v[204:207], v[76:79]
	v_mfma_f32_16x16x32_bf16 v[72:75], v[180:183], v[204:207], v[72:75]
	v_mfma_f32_16x16x32_bf16 v[68:71], v[172:175], v[212:215], v[68:71]
	v_mfma_f32_16x16x32_bf16 v[64:67], v[180:183], v[212:215], v[64:67]
	v_mfma_f32_16x16x32_bf16 v[108:111], v[176:179], v[192:195], v[108:111]
	v_mfma_f32_16x16x32_bf16 v[100:103], v[184:187], v[192:195], v[100:103]
	v_mfma_f32_16x16x32_bf16 v[92:95], v[176:179], v[200:203], v[92:95]
	v_mfma_f32_16x16x32_bf16 v[84:87], v[184:187], v[200:203], v[84:87]
	v_mfma_f32_16x16x32_bf16 v[76:79], v[176:179], v[208:211], v[76:79]
	v_mfma_f32_16x16x32_bf16 v[72:75], v[184:187], v[208:211], v[72:75]
	v_mfma_f32_16x16x32_bf16 v[68:71], v[176:179], v[216:219], v[68:71]
	v_mfma_f32_16x16x32_bf16 v[64:67], v[184:187], v[216:219], v[64:67]
	s_setprio 0
	s_barrier
; #define PG8_STAGE(bufoff, gbase, voff) do { _Pragma("unroll") for (int _i = 0; _i < 2; ++_i) \
;         __builtin_amdgcn_global_load_lds((const unsigned*)((const char*)(gbase) + (voff)[_i]), (LAS unsigned*)(lds + (bufoff) + ldsw + _i * 8192), 16, 0, 0); } while (0)
; #define PG8_LDA(dst, b, h) do { _Pragma("unroll") for (int m = 0; m < 4; ++m) _Pragma("unroll") for (int k = 0; k < 2; ++k) dst[m][k] = *(const LAS bf16x8*)(lds + PG8_SA(b, h) + aoff + m * 2048 + k * 1024); } while (0)
; #define PG8_MMA(ai, bj, At, Bt) do { __builtin_amdgcn_s_setprio(1); _Pragma("unroll") for (int m = 0; m < 4; ++m) _Pragma("unroll") for (int n = 0; n < 2; ++n) _Pragma("unroll") for (int k = 0; k < 2; ++k) \
;         acc[ai][bj][m][n] = __builtin_amdgcn_mfma_f32_16x16x32_bf16(Bt[n][k], At[m][k], acc[ai][bj][m][n], 0, 0, 0); __builtin_amdgcn_s_setprio(0); } while (0)
; #define PG8_WAIT_V(n) asm volatile("s_waitcnt vmcnt(" #n ")" ::: "memory")
; #define PG8_WAIT_L(n) asm volatile("s_waitcnt lgkmcnt(" #n ")" ::: "memory")
; #define PG8_BAR __builtin_amdgcn_s_barrier()
; #define PG8_SCHED __builtin_amdgcn_sched_barrier(0)
; template <class Epi, class Sched>
; __device__ __forceinline__ void gemm_phase(LAS unsigned char* lds, const Sched& S, const Epi& E, bool natural = false) {
;     ...
;             PG8_LDA(At, 1, 1); PG8_STAGE(PG8_SB(1, 0), b3, voffB0); PG8_STAGE(PG8_SB(1, 1), b3, voffB1); PG8_STAGE(PG8_SA(1, 0), a3, voffA);
;             PG8_WAIT_V(8); PG8_WAIT_L(0); PG8_BAR; PG8_MMA(1, 0, At, B0); PG8_MMA(1, 1, At, B1); PG8_BAR; PG8_SCHED;
;         }
	s_add_u32 s22, s22, 0x80
	s_addc_u32 s23, s23, 0
	s_add_i32 s24, s57, s31
	v_lshl_add_u64 v[220:221], v[220:221], 0, s[8:9]
	s_mov_b32 m0, s24
	ds_read_b128 v[188:191], v158 offset:49152
	ds_read_b128 v[192:195], v158 offset:50176
	ds_read_b128 v[196:199], v158 offset:51200
	ds_read_b128 v[200:203], v158 offset:52224
	ds_read_b128 v[204:207], v158 offset:53248
	ds_read_b128 v[208:211], v158 offset:54272
	ds_read_b128 v[212:215], v158 offset:55296
	ds_read_b128 v[216:219], v158 offset:56320
	global_load_lds_dwordx4 v[220:221], off
	v_lshl_add_u64 v[220:221], v[222:223], 0, s[8:9]
	s_add_i32 m0, s24, 0x2000
	s_add_i32 s24, s58, s31
	global_load_lds_dwordx4 v[220:221], off
	v_lshl_add_u64 v[220:221], s[22:23], 0, v[134:135]
	s_mov_b32 m0, s24
	s_nop 0
	global_load_lds_dwordx4 v[220:221], off
	v_lshl_add_u64 v[220:221], s[22:23], 0, v[128:129]
	s_add_i32 m0, s24, 0x2000
	s_nop 0
	global_load_lds_dwordx4 v[220:221], off
	v_lshl_add_u64 v[220:221], v[224:225], 0, s[8:9]
	s_mov_b32 m0, s41
	s_nop 0
	global_load_lds_dwordx4 v[220:221], off
	v_lshl_add_u64 v[220:221], v[226:227], 0, s[8:9]
	s_mov_b32 m0, s42
	s_nop 0
	global_load_lds_dwordx4 v[220:221], off
	s_waitcnt vmcnt(8)
	s_waitcnt lgkmcnt(0)
	s_barrier
	s_setprio 1
	s_waitcnt lgkmcnt(0)
	v_mfma_f32_16x16x32_bf16 v[60:63], v[150:153], v[188:191], v[60:63]
	v_mfma_f32_16x16x32_bf16 v[56:59], v[164:167], v[188:191], v[56:59]
	v_mfma_f32_16x16x32_bf16 v[52:55], v[150:153], v[196:199], v[52:55]
	v_mfma_f32_16x16x32_bf16 v[48:51], v[164:167], v[196:199], v[48:51]
	v_mfma_f32_16x16x32_bf16 v[44:47], v[150:153], v[204:207], v[44:47]
	v_mfma_f32_16x16x32_bf16 v[32:35], v[164:167], v[204:207], v[32:35]
	v_mfma_f32_16x16x32_bf16 v[20:23], v[150:153], v[212:215], v[20:23]
	v_mfma_f32_16x16x32_bf16 v[8:11], v[164:167], v[212:215], v[8:11]
	v_mfma_f32_16x16x32_bf16 v[60:63], v[160:163], v[192:195], v[60:63]
	v_mfma_f32_16x16x32_bf16 v[56:59], v[168:171], v[192:195], v[56:59]
	v_mfma_f32_16x16x32_bf16 v[52:55], v[160:163], v[200:203], v[52:55]
	v_mfma_f32_16x16x32_bf16 v[48:51], v[168:171], v[200:203], v[48:51]
	v_mfma_f32_16x16x32_bf16 v[44:47], v[160:163], v[208:211], v[44:47]
	v_mfma_f32_16x16x32_bf16 v[32:35], v[168:171], v[208:211], v[32:35]
	v_mfma_f32_16x16x32_bf16 v[20:23], v[160:163], v[216:219], v[20:23]
	v_mfma_f32_16x16x32_bf16 v[8:11], v[168:171], v[216:219], v[8:11]
	s_setprio 0
	s_setprio 1
	v_mfma_f32_16x16x32_bf16 v[40:43], v[172:175], v[188:191], v[40:43]
	v_mfma_f32_16x16x32_bf16 v[36:39], v[180:183], v[188:191], v[36:39]
	v_mfma_f32_16x16x32_bf16 v[28:31], v[172:175], v[196:199], v[28:31]
	v_mfma_f32_16x16x32_bf16 v[24:27], v[180:183], v[196:199], v[24:27]
	v_mfma_f32_16x16x32_bf16 v[16:19], v[172:175], v[204:207], v[16:19]
	v_mfma_f32_16x16x32_bf16 v[12:15], v[180:183], v[204:207], v[12:15]
	v_mfma_f32_16x16x32_bf16 v[4:7], v[172:175], v[212:215], v[4:7]
	v_mfma_f32_16x16x32_bf16 v[0:3], v[180:183], v[212:215], v[0:3]
	v_mfma_f32_16x16x32_bf16 v[40:43], v[176:179], v[192:195], v[40:43]
	v_mfma_f32_16x16x32_bf16 v[36:39], v[184:187], v[192:195], v[36:39]
	v_mfma_f32_16x16x32_bf16 v[28:31], v[176:179], v[200:203], v[28:31]
	v_mfma_f32_16x16x32_bf16 v[24:27], v[184:187], v[200:203], v[24:27]
	v_mfma_f32_16x16x32_bf16 v[16:19], v[176:179], v[208:211], v[16:19]
	v_mfma_f32_16x16x32_bf16 v[12:15], v[184:187], v[208:211], v[12:15]
	v_mfma_f32_16x16x32_bf16 v[4:7], v[176:179], v[216:219], v[4:7]
	v_mfma_f32_16x16x32_bf16 v[0:3], v[184:187], v[216:219], v[0:3]
	s_setprio 0
	s_barrier
	s_add_i32 s56, s56, 2
	s_add_u32 s20, s20, 0x100
	s_addc_u32 s21, s21, 0
	s_add_u32 s54, s54, 0x100
	s_addc_u32 s55, s55, 0
	s_cmp_gt_u32 s56, 13
	s_cbranch_scc0 .LBB0_564
